# scan DPP ops: 2 wait states after every VALU write feeding a DPP instruction (also non-shifted operands), per the compiler's hazard rule
# baseline (speedup 1.0000x reference)
.Lrnn_halo_ld:
	s_or_b64 exec, exec, s[10:11]
	s_waitcnt lgkmcnt(7)
	v_fma_f32 v149, 0, v148, v149
	v_fma_f32 v156, v150, v149, v151
	v_mul_f32_e32 v157, v148, v150
	s_waitcnt lgkmcnt(6)
	v_fma_f32 v158, v152, v156, v153
	v_mul_f32_e32 v159, v157, v152
	v_mul_f32_e32 v160, v154, v159
	v_fmac_f32_e32 v155, v154, v158
	s_waitcnt lgkmcnt(5)
	v_fma_f32 v145, v144, v155, v145
	v_mul_f32_e32 v144, v144, v160
	v_mul_f32_e32 v154, v146, v144
	v_fmac_f32_e32 v147, v146, v145
	s_waitcnt lgkmcnt(4)
	v_fma_f32 v141, v140, v147, v141
	v_mul_f32_e32 v140, v140, v154
	v_mul_f32_e32 v146, v142, v140
	v_fmac_f32_e32 v143, v142, v141
	v_mov_b32_e32 v150, v143
	v_mov_b32_e32 v142, v146
	v_mov_b32_e32 v151, 1.0
	s_nop 1
	v_fmac_f32_dpp v150, v150, v142 row_shr:1 row_mask:0xf bank_mask:0xf
	v_mul_f32_dpp v142, v142, v142 row_shr:1 row_mask:0xf bank_mask:0xf
	s_nop 1
	v_fmac_f32_dpp v150, v150, v142 row_shr:2 row_mask:0xf bank_mask:0xf
	v_mul_f32_dpp v142, v142, v142 row_shr:2 row_mask:0xf bank_mask:0xf
	s_nop 1
	v_fmac_f32_dpp v150, v150, v142 row_shr:4 row_mask:0xf bank_mask:0xf
	v_mul_f32_dpp v142, v142, v142 row_shr:4 row_mask:0xf bank_mask:0xf
	s_nop 1
	v_fmac_f32_dpp v150, v150, v142 row_shr:8 row_mask:0xf bank_mask:0xf
	v_mul_f32_dpp v142, v142, v142 row_shr:8 row_mask:0xf bank_mask:0xf
	s_nop 0
	v_mov_b32_dpp v161, v150 row_shr:1 row_mask:0xf bank_mask:0xf
	v_mov_b32_dpp v151, v142 row_shr:1 row_mask:0xf bank_mask:0xf
	v_fmac_f32_e32 v150, v142, v225
	v_fmac_f32_e32 v161, v151, v225
	ds_bpermute_b32 v225, v196, v150
	ds_read_b128 v[150:153], v226
	v_fmac_f32_e32 v145, v144, v161
	v_fmac_f32_e32 v149, v148, v161
	v_fmac_f32_e32 v147, v154, v161
	v_fmac_f32_e32 v141, v140, v161
	s_waitcnt lgkmcnt(0)
	v_lshlrev_b32_e32 v163, 16, v152
	v_lshlrev_b32_e32 v142, 16, v150
	v_mul_f32_e32 v144, v145, v163
	v_mul_f32_e32 v145, 0xbfb8aa3b, v163
	v_mul_f32_e32 v148, v149, v142
	v_mul_f32_e32 v142, 0xbfb8aa3b, v142
	v_exp_f32_e32 v145, v145
	v_exp_f32_e32 v142, v142
	v_and_b32_e32 v150, 0xffff0000, v150
	v_and_b32_e32 v152, 0xffff0000, v152
	v_add_f32_e32 v145, 1.0, v145
	v_add_f32_e32 v142, 1.0, v142
	v_rcp_f32_e32 v145, v145
	v_rcp_f32_e32 v142, v142
	v_lshlrev_b32_e32 v164, 16, v153
	v_lshlrev_b32_e32 v162, 16, v151
	v_fmac_f32_e32 v156, v157, v161
	v_mul_f32_e32 v149, 0xbfb8aa3b, v150
	v_mul_f32_e32 v144, v144, v145
	v_mul_f32_e32 v145, v147, v152
	v_mul_f32_e32 v147, 0xbfb8aa3b, v152
	v_mul_f32_e32 v140, v141, v164
	v_mul_f32_e32 v141, 0xbfb8aa3b, v164
	v_mul_f32_e32 v142, v148, v142
	v_mul_f32_e32 v148, v156, v150
	v_exp_f32_e32 v149, v149
	v_mul_f32_e32 v150, 0xbfb8aa3b, v162
	v_exp_f32_e32 v147, v147
	v_exp_f32_e32 v141, v141
	v_exp_f32_e32 v150, v150
	v_add_f32_e32 v149, 1.0, v149
	v_add_f32_e32 v147, 1.0, v147
	v_add_f32_e32 v141, 1.0, v141
	v_rcp_f32_e32 v149, v149
	v_add_f32_e32 v150, 1.0, v150
	v_rcp_f32_e32 v147, v147
	v_rcp_f32_e32 v141, v141
	v_rcp_f32_e32 v150, v150
	v_and_b32_e32 v153, 0xffff0000, v153
	v_fmac_f32_e32 v158, v159, v161
	v_and_b32_e32 v151, 0xffff0000, v151
	v_mul_f32_e32 v148, v148, v149
	v_mul_f32_e32 v149, v158, v162
	v_fmac_f32_e32 v155, v160, v161
	v_mul_f32_e32 v145, v145, v147
	v_mul_f32_e32 v147, v140, v141
	v_mul_f32_e32 v141, 0xbfb8aa3b, v153
	v_mul_f32_e32 v149, v149, v150
	v_mul_f32_e32 v150, v155, v151
	v_mul_f32_e32 v151, 0xbfb8aa3b, v151
	v_exp_f32_e32 v141, v141
	v_exp_f32_e32 v151, v151
	v_fmac_f32_e32 v143, v146, v161
	v_mul_f32_e32 v140, v143, v153
	v_add_f32_e32 v141, 1.0, v141
	v_add_f32_e32 v151, 1.0, v151
	v_rcp_f32_e32 v141, v141
	v_rcp_f32_e32 v151, v151
	v_mul_f32_e32 v143, v140, v141
	v_mul_f32_e32 v150, v150, v151
	v_cvt_pk_bf16_f32 v140, v142, v148
	v_cvt_pk_bf16_f32 v141, v149, v150
	v_cvt_pk_bf16_f32 v142, v144, v145
	v_cvt_pk_bf16_f32 v143, v147, v143
	ds_write_b128 v227, v[140:143]
	s_branch .LBB0_112
